# code placement: + attention loop body (first block in text order) aligned to 64 bytes
# baseline (speedup 1.0000x reference)
; #define LAS __attribute__((address_space(3)))
; __device__ __forceinline__ void attn_wave(LAS unsigned char* wl, const bf16* Q, const bf16* K, const bf16* V, bf16* O, const float* relb, int b, int n, int h, int lane) {
;     ...
;     const int trb = (4 * hf + ((lane & 15) >> 2)) * 192 + (16 * ((lane >> 4) & 1) + 4 * (lane & 3)) * 2;
;     LAS float* biasL = (LAS float*)(wl + 6144);
;     for (int i = lane; i < 257; i += 64) biasL[i] = relb[h * 257 + i] * 1.4426950408889634f;
;     const size_t tq0 = (size_t)b * SEQ + (size_t)n * 64;
;     bf16x8 qf[2][4];
; #pragma unroll
;     for (int qb = 0; qb < 2; ++qb)
; #pragma unroll
;         for (int ks = 0; ks < 4; ++ks) qf[qb][ks] = *(const bf16x8*)(Q + (tq0 + 32 * qb + r32) * AW + h * 64 + 16 * ks + 8 * hf);
;     f32x16 o[2][2];
; #pragma unroll
;     for (int db = 0; db < 2; ++db)
; #pragma unroll
;         for (int qb = 0; qb < 2; ++qb)
; #pragma unroll
;             for (int i = 0; i < 16; ++i) o[db][qb][i] = 0.f;
;     float mrun[2] = {-INFINITY, -INFINITY}, lrun[2] = {0.f, 0.f};
;     const float CL2 = 0.125f * 1.4426950408889634f;
;     const int kk0 = n >= 8 ? 0 : 2 * (8 - n);
;     const bf16* kp = K + ((size_t)b * SEQ + (size_t)(n - 8) * 64 + r32) * AW + h * 64 + 8 * hf;
;     const bf16* vp = V + ((size_t)b * SEQ + (size_t)(n - 8) * 64 + (lane >> 3)) * AW + h * 64 + 8 * (lane & 7);
;     bf16x8 kf[4]; v4u vr[4];
; #pragma unroll
;     for (int ks = 0; ks < 4; ++ks) kf[ks] = *(const bf16x8*)(kp + (size_t)kk0 * 32 * AW + 16 * ks);
; #pragma unroll
;     for (int i = 0; i < 4; ++i) vr[i] = *(const v4u*)(vp + ((size_t)kk0 * 32 + 8 * i) * AW);
;     for (int kk = kk0; kk < 18; ++kk) {
; __global__ void __launch_bounds__(512, 2) hybrid_fwd(Args args) {
;     ...
;         for (int u0 = blk; u0 < BATCH * NCHUNK; u0 += G) {
;             const int unit = (u0 & 7) * (BATCH * NCHUNK / 8) + (u0 >> 3);
;             const int b = unit / NCHUNK, n = unit % NCHUNK;
;             attn_wave(lds + wave * 8192, QB, KB, VB, ATT, rel_bias, b, n, wave, lane);
.LBB0_553:
	s_or_b64 exec, exec, s[0:1]
	v_mov_b32_e32 v253, s53
	ds_read_b32 v254, v253 offset:7168
	v_mbcnt_lo_u32_b32 v255, -1, 0
	v_mbcnt_hi_u32_b32 v255, -1, v255
	v_lshl_add_u32 v255, v255, 2, s53
	s_waitcnt lgkmcnt(0)
	ds_write_b32 v255, v254 offset:7172
	s_lshl_b32 s0, s80, 5
	s_and_b32 s0, s0, 0xe0
	s_ashr_i32 s1, s80, 3
	s_add_i32 s0, s0, s1
	s_ashr_i32 s1, s0, 31
	s_lshr_b32 s1, s1, 25
	s_add_i32 s1, s0, s1
	s_ashr_i32 s14, s1, 7
	s_and_b32 s1, s1, 0xffffff80
	s_sub_i32 s16, s0, s1
	s_ashr_i32 s15, s14, 31
	s_ashr_i32 s17, s16, 31
	s_lshl_b64 s[0:1], s[14:15], 13
	s_lshl_b64 s[18:19], s[16:17], 6
	s_add_u32 s17, s18, s0
	s_addc_u32 s20, s19, s1
	s_lshl_b32 s21, s16, 1
	s_sub_i32 s21, 16, s21
	s_cmp_lt_i32 s16, 8
	v_mov_b32_e32 v1, s20
	v_or_b32_e32 v0, s17, v164
	s_cselect_b32 s44, s21, 0
	v_lshlrev_b64 v[186:187], 10, v[0:1]
	v_mov_b32_e32 v189, 0
	s_cmp_lt_i32 s44, 18
	v_mov_b32_e32 v188, 0
	v_mov_b32_e32 v63, 0
	v_mov_b32_e32 v62, 0
	v_mov_b32_e32 v61, 0
	v_mov_b32_e32 v60, 0
	v_mov_b32_e32 v59, 0
	v_mov_b32_e32 v58, 0
	v_mov_b32_e32 v57, 0
	v_mov_b32_e32 v56, 0
	v_mov_b32_e32 v55, 0
	v_mov_b32_e32 v54, 0
	v_mov_b32_e32 v53, 0
	v_mov_b32_e32 v52, 0
	v_mov_b32_e32 v51, 0
	v_mov_b32_e32 v50, 0
	v_mov_b32_e32 v49, 0
	v_mov_b32_e32 v48, 0
	v_mov_b32_e32 v31, 0
	v_mov_b32_e32 v30, 0
	v_mov_b32_e32 v29, 0
	v_mov_b32_e32 v28, 0
	v_mov_b32_e32 v27, 0
	v_mov_b32_e32 v26, 0
	v_mov_b32_e32 v25, 0
	v_mov_b32_e32 v24, 0
	v_mov_b32_e32 v23, 0
	v_mov_b32_e32 v22, 0
	v_mov_b32_e32 v21, 0
	v_mov_b32_e32 v20, 0
	v_mov_b32_e32 v19, 0
	v_mov_b32_e32 v18, 0
	v_mov_b32_e32 v17, 0
	v_mov_b32_e32 v16, 0
	v_mov_b32_e32 v47, 0
	v_mov_b32_e32 v46, 0
	v_mov_b32_e32 v45, 0
	v_mov_b32_e32 v44, 0
	v_mov_b32_e32 v43, 0
	v_mov_b32_e32 v42, 0
	v_mov_b32_e32 v41, 0
	v_mov_b32_e32 v40, 0
	v_mov_b32_e32 v39, 0
	v_mov_b32_e32 v38, 0
	v_mov_b32_e32 v37, 0
	v_mov_b32_e32 v36, 0
	v_mov_b32_e32 v35, 0
	v_mov_b32_e32 v34, 0
	v_mov_b32_e32 v33, 0
	v_mov_b32_e32 v32, 0
	v_mov_b32_e32 v15, 0
	v_mov_b32_e32 v14, 0
	v_mov_b32_e32 v13, 0
	v_mov_b32_e32 v12, 0
	v_mov_b32_e32 v11, 0
	v_mov_b32_e32 v10, 0
	v_mov_b32_e32 v9, 0
	v_mov_b32_e32 v8, 0
	v_mov_b32_e32 v7, 0
	v_mov_b32_e32 v6, 0
	v_mov_b32_e32 v5, 0
	v_mov_b32_e32 v4, 0
	v_mov_b32_e32 v3, 0
	v_mov_b32_e32 v2, 0
	v_mov_b32_e32 v1, 0
	v_mov_b32_e32 v0, 0
	s_cbranch_scc0 .LBB0_564
	v_lshl_add_u64 v[0:1], v[166:167], 0, v[186:187]
	s_add_u32 s0, s18, s0
	global_load_dwordx4 v[96:99], v[0:1], off
	global_load_dwordx4 v[100:103], v[0:1], off offset:32
	global_load_dwordx4 v[104:107], v[0:1], off offset:64
	global_load_dwordx4 v[108:111], v[0:1], off offset:96
	v_mov_b32_e32 v1, s20
	v_or_b32_e32 v0, s17, v170
	s_addc_u32 s1, s19, s1
	v_lshlrev_b64 v[0:1], 10, v[0:1]
	s_add_u32 s0, s0, 0xfffffe00
	v_lshl_add_u64 v[0:1], v[166:167], 0, v[0:1]
	s_addc_u32 s1, s1, -1
	global_load_dwordx4 v[112:115], v[0:1], off
	global_load_dwordx4 v[116:119], v[0:1], off offset:32
	global_load_dwordx4 v[120:123], v[0:1], off offset:64
	global_load_dwordx4 v[124:127], v[0:1], off offset:96
	v_mov_b32_e32 v1, s1
	v_or_b32_e32 v0, s0, v164
	v_lshlrev_b64 v[0:1], 10, v[0:1]
	v_lshl_add_u64 v[190:191], v[172:173], 0, v[0:1]
	v_lshl_add_u64 v[0:1], s[0:1], 0, v[174:175]
	v_lshlrev_b64 v[0:1], 10, v[0:1]
	v_lshl_add_u64 v[192:193], v[176:177], 0, v[0:1]
	s_lshl_b64 s[0:1], s[44:45], 15
	v_lshl_add_u64 v[0:1], v[192:193], 0, s[0:1]
	v_add_co_u32_e32 v2, vcc, s75, v0
	v_mov_b32_e32 v14, v168
	s_nop 0
	v_addc_co_u32_e32 v3, vcc, 0, v1, vcc
	v_add_co_u32_e32 v4, vcc, s76, v0
	v_mov_b32_e32 v15, v168
	s_nop 0
	v_addc_co_u32_e32 v5, vcc, 0, v1, vcc
	v_add_co_u32_e32 v6, vcc, s77, v0
	v_mov_b32_e32 v169, v168
	s_nop 0
	v_addc_co_u32_e32 v7, vcc, 0, v1, vcc
	global_load_dwordx4 v[152:155], v[4:5], off
	global_load_dwordx4 v[148:151], v[6:7], off
	global_load_dwordx4 v[156:159], v[2:3], off
	global_load_dwordx4 v[144:147], v[0:1], off
	v_lshl_add_u64 v[0:1], v[190:191], 0, s[0:1]
	global_load_dwordx4 v[128:131], v[0:1], off offset:96
	global_load_dwordx4 v[132:135], v[0:1], off offset:64
	global_load_dwordx4 v[136:139], v[0:1], off offset:32
	global_load_dwordx4 v[140:143], v[0:1], off
	v_and_b32_e32 v1, 64, v233
	v_xor_b32_e32 v0, 32, v233
	v_add_u32_e32 v1, 64, v1
	v_cmp_lt_i32_e32 vcc, v0, v1
	s_lshl_b32 s0, s44, 5
	v_mov_b32_e32 v1, v168
	v_cndmask_b32_e32 v0, v233, v0, vcc
	v_lshlrev_b32_e32 v234, 2, v0
	v_mov_b32_e32 v0, v168
	v_mov_b32_e32 v2, v168
	v_mov_b32_e32 v3, v168
	v_mov_b32_e32 v4, v168
	v_mov_b32_e32 v5, v168
	v_mov_b32_e32 v6, v168
	v_mov_b32_e32 v7, v168
	v_mov_b32_e32 v8, v168
	v_mov_b32_e32 v9, v168
	v_mov_b32_e32 v10, v168
	v_mov_b32_e32 v11, v168
	v_mov_b32_e32 v12, v168
	v_mov_b32_e32 v13, v168
	v_mov_b64_e32 v[46:47], v[14:15]
	v_mov_b64_e32 v[30:31], v[14:15]
	v_mov_b64_e32 v[62:63], v[14:15]
	v_subrev_u32_e32 v235, s0, v230
	s_add_i32 s17, s44, -1
	v_mov_b32_e32 v236, 0xff800000
	v_mov_b64_e32 v[44:45], v[12:13]
	v_mov_b64_e32 v[42:43], v[10:11]
	v_mov_b64_e32 v[40:41], v[8:9]
	v_mov_b64_e32 v[38:39], v[6:7]
	v_mov_b64_e32 v[36:37], v[4:5]
	v_mov_b64_e32 v[34:35], v[2:3]
	v_mov_b64_e32 v[32:33], v[0:1]
	v_mov_b64_e32 v[28:29], v[12:13]
	v_mov_b64_e32 v[26:27], v[10:11]
	v_mov_b64_e32 v[24:25], v[8:9]
	v_mov_b64_e32 v[22:23], v[6:7]
	v_mov_b64_e32 v[20:21], v[4:5]
	v_mov_b64_e32 v[18:19], v[2:3]
	v_mov_b64_e32 v[16:17], v[0:1]
	v_mov_b64_e32 v[60:61], v[12:13]
	v_mov_b64_e32 v[58:59], v[10:11]
	v_mov_b64_e32 v[56:57], v[8:9]
	v_mov_b64_e32 v[54:55], v[6:7]
	v_mov_b64_e32 v[52:53], v[4:5]
	v_mov_b64_e32 v[50:51], v[2:3]
	v_mov_b64_e32 v[48:49], v[0:1]
	v_mov_b32_e32 v237, 0xff800000
	v_mov_b64_e32 v[188:189], v[168:169]
	s_branch .LBB0_556
	.p2align	6
